# early gating units with a split-phase seam: those workgroups arrive at the projection seam first, run the unit, then wait for the release
# baseline (speedup 1.0000x reference)
; __device__ __forceinline__ unsigned xb_ld(unsigned* p)              { return __hip_atomic_load(p, __ATOMIC_RELAXED, __HIP_MEMORY_SCOPE_AGENT); }
; __device__ __forceinline__ unsigned xb_add(unsigned* p, unsigned v) { return __hip_atomic_fetch_add(p, v, __ATOMIC_RELAXED, __HIP_MEMORY_SCOPE_AGENT); }
; #define XB_SPIN(cond, bar) do { unsigned _sp = 0; while (cond) { __builtin_amdgcn_s_sleep(8); \
;     if ((++_sp & 255u) == 0u) { if (xb_ld(&(bar)[XB_TMO])) break; if (_sp > XB_SPIN_CAP) { atomicAdd(&(bar)[XB_TMO], 1u); break; } } } } while (0)
; __device__ __forceinline__ void xcd_barrier(const XcdBarrier& b) {
;     ...
;         unsigned nloc = b.st[0], nx = b.st[1];
;         if (nloc == 0u) { xcd_barrier_complete(bar, b.x, nloc, nx); b.st[0] = nloc; b.st[1] = nx; }
;         const unsigned old = xb_add(&bar[XB_XSUB(b.x)], 1u);
;         const unsigned gen = old / nloc;
;         if (old + 1u == (gen + 1u) * nloc) {
;             __builtin_amdgcn_fence(__ATOMIC_RELEASE, "agent");
;             asm volatile("s_waitcnt vmcnt(0)" ::: "memory");
;             const unsigned og = xb_add(&bar[XB_TOP], 1u);
;             const unsigned tg = og / nx;
;             if (og + 1u == (tg + 1u) * nx) xb_add(&bar[XB_TOPGEN], 1u);
;             else XB_SPIN(xb_ld(&bar[XB_TOPGEN]) == tg, bar);
;             __builtin_amdgcn_fence(__ATOMIC_ACQUIRE, "agent");
;             xb_add(&bar[XB_XGEN(b.x)], 1u);
;             asm volatile("s_waitcnt vmcnt(0)" ::: "memory");
;         } else {
;             XB_SPIN(xb_ld(&bar[XB_XGEN(b.x)]) == gen, bar);
;             __builtin_amdgcn_fence(__ATOMIC_ACQUIRE, "agent");
;             asm volatile("s_waitcnt vmcnt(0)" ::: "memory");
;         }
.LBB0_1042:
	s_or_b64 exec, exec, s[30:31]
	v_cvt_f32_u32_e32 v5, v3
	s_waitcnt vmcnt(0)
	v_readfirstlane_b32 s4, v4
	v_sub_u32_e32 v4, 0, v3
	v_rcp_iflag_f32_e32 v5, v5
	v_add_u32_e32 v6, s4, v0
	v_mul_f32_e32 v5, 0x4f7ffffe, v5
	v_cvt_u32_f32_e32 v5, v5
	v_mul_lo_u32 v0, v4, v5
	v_mul_hi_u32 v0, v5, v0
	v_add_u32_e32 v0, v5, v0
	v_mul_hi_u32 v0, v6, v0
	v_mul_lo_u32 v4, v0, v3
	v_sub_u32_e32 v4, v6, v4
	v_add_u32_e32 v5, 1, v0
	v_cmp_ge_u32_e32 vcc, v4, v3
	s_nop 1
	v_cndmask_b32_e32 v0, v0, v5, vcc
	v_sub_u32_e32 v5, v4, v3
	v_cndmask_b32_e32 v4, v4, v5, vcc
	v_add_u32_e32 v5, 1, v0
	v_cmp_ge_u32_e32 vcc, v4, v3
	v_add_u32_e32 v4, 1, v6
	s_nop 0
	v_cndmask_b32_e32 v0, v0, v5, vcc
	v_mul_lo_u32 v5, v3, v0
	v_add_u32_e32 v3, v5, v3
	v_cmp_ne_u32_e32 vcc, v4, v3
	s_and_saveexec_b64 s[4:5], vcc
	s_xor_b64 s[30:31], exec, s[4:5]
	s_cbranch_execz .LBB0_1056
	s_cmp_lt_u32 s2, 0x80
	s_cbranch_scc1 .Lsp_a_no
	v_mov_b32_e32 v5, 0x23084
	ds_read_b32 v5, v5
	s_waitcnt lgkmcnt(0)
	v_cmp_eq_u32_e32 vcc, 0, v5
	s_cbranch_vccnz .Lsp_a_no
	v_mov_b32_e32 v5, 0x230b0
	v_mov_b32_e32 v6, 1
	ds_write2_b32 v5, v0, v6 offset1:1
	s_waitcnt lgkmcnt(0)
	s_branch .LBB0_1056
.Lsp_a_no:
	v_readlane_b32 s4, v252, 49
	v_readlane_b32 s5, v252, 50
	s_waitcnt lgkmcnt(0)
	s_nop 3
	global_load_dword v2, v1, s[4:5] sc1
	s_waitcnt vmcnt(0)
	v_cmp_eq_u32_e32 vcc, v2, v0
	s_and_saveexec_b64 s[42:43], vcc
	s_cbranch_execz .LBB0_1055
	s_mov_b32 s4, 1
	s_mov_b64 s[44:45], 0
	s_branch .LBB0_1046

; #define SEAM(k) do { if ((k) + 1 < hi) { if ((k) == 0) grid.sync(); else { xcd_barrier(bar); if (DUP & 4) xcd_barrier(bar); } } } while (0)
; #define SEAM(k) do { } while (0)
; __device__ __forceinline__ void xcd_barrier(const XcdBarrier& b) {
;     ...
;     __syncthreads();
; }
; __global__ void __launch_bounds__(NWAVES * 64, 2) fwd_kernel(Args a) {
;     ...
;                 IDLE_CONVERT(1);
;                 SEAM(pb + 2);
.LBB0_1076:
	s_or_b64 exec, exec, s[28:29]
	s_waitcnt lgkmcnt(0)
	s_barrier
	s_cmp_lt_u32 s2, 0x80
	s_cbranch_scc1 .Lsp_done
	v_mov_b32_e32 v0, 0x23084
	ds_read_b32 v0, v0
	s_waitcnt lgkmcnt(0)
	v_readfirstlane_b32 s4, v0
	s_nop 3
	s_cmp_eq_u32 s4, 0
	s_cbranch_scc1 .Lsp_done
	s_waitcnt vmcnt(0)
	s_mov_b64 s[4:5], exec
	v_readlane_b32 s6, v254, 7
	v_readlane_b32 s7, v254, 8
	s_nop 1
	s_and_b64 exec, s[4:5], s[6:7]
	s_cbranch_execz .Les_polled
	v_readlane_b32 s6, v252, 34
	v_readlane_b32 s7, v252, 35
	s_and_b32 s8, s2, 7
	s_lshl_b32 s8, s8, 3
	s_bfe_u32 s9, s2, 0x30004
	s_or_b32 s8, s8, s9
	s_lshl_b32 s8, s8, 5
	s_addk_i32 s8, 0x3610
	s_add_u32 s6, s6, s8
	s_addc_u32 s7, s7, 0
	v_mov_b32_e32 v2, 0x230a4
	v_mov_b32_e32 v3, 4
	ds_add_rtn_u32 v5, v2, v3
	v_mov_b32_e32 v2, 0
	s_waitcnt lgkmcnt(0)
	v_add_u32_e32 v5, 4, v5
	s_mov_b32 s8, 0

; __device__ __forceinline__ unsigned xb_ld(unsigned* p)              { return __hip_atomic_load(p, __ATOMIC_RELAXED, __HIP_MEMORY_SCOPE_AGENT); }
; __device__ __forceinline__ unsigned xb_add(unsigned* p, unsigned v) { return __hip_atomic_fetch_add(p, v, __ATOMIC_RELAXED, __HIP_MEMORY_SCOPE_AGENT); }
; #define XB_SPIN(cond, bar) do { unsigned _sp = 0; while (cond) { __builtin_amdgcn_s_sleep(8); \
;     if ((++_sp & 255u) == 0u) { if (xb_ld(&(bar)[XB_TMO])) break; if (_sp > XB_SPIN_CAP) { atomicAdd(&(bar)[XB_TMO], 1u); break; } } } } while (0)
; #define WSBASE() GAS unsigned char* wsg_ = (GAS unsigned char*)a.ws; asm volatile("" : "+s"(wsg_)); unsigned char* ws = (unsigned char*)wsg_; i64* stats = (i64*)(ws + WS_STATS); i64* st = stats + (size_t)(6 * l) * MTOK; unsigned char* wl = ws + WS_W + (size_t)l * WL_STRIDE; (void)st; (void)wl
; __device__ __forceinline__ void xcd_barrier(const XcdBarrier& b) {
;     ...
;             else XB_SPIN(xb_ld(&bar[XB_TOPGEN]) == tg, bar);
;             __builtin_amdgcn_fence(__ATOMIC_ACQUIRE, "agent");
;             xb_add(&bar[XB_XGEN(b.x)], 1u);
;             asm volatile("s_waitcnt vmcnt(0)" ::: "memory");
;         } else {
;             XB_SPIN(xb_ld(&bar[XB_XGEN(b.x)]) == gen, bar);
;             __builtin_amdgcn_fence(__ATOMIC_ACQUIRE, "agent");
;             asm volatile("s_waitcnt vmcnt(0)" ::: "memory");
;         }
;     }
;     __syncthreads();
; }
; __global__ void __launch_bounds__(NWAVES * 64, 2) fwd_kernel(Args a) {
;     ...
;             if (IN(pb + 3)) {
;                 const int tid = threadIdx.x, lane = tid & 63, wave = __builtin_amdgcn_readfirstlane(tid >> 6);
;                 if (!(SKIP & 4)) { WSBASE();
;                   for (int u = cu; u < 256; u += G) { const int j = u >> 3, bh = (u & 7) * 2 + (j >> 4), blk = j & 15;
.Lin_seam:
	s_mov_b64 s[4:5], exec
	v_readlane_b32 s6, v254, 7
	v_readlane_b32 s7, v254, 8
	s_nop 1
	s_and_b64 exec, s[4:5], s[6:7]
	s_cbranch_execz .Lsp_c_skip
	v_mov_b32_e32 v2, 0x230b0
	ds_read_b64 v[2:3], v2
	s_waitcnt lgkmcnt(0)
	v_cmp_eq_u32_e32 vcc, 0, v3
	s_cbranch_vccnz .Lsp_c_skip
	v_readlane_b32 s6, v252, 49
	v_readlane_b32 s7, v252, 50
	v_mov_b32_e32 v5, 0
	s_mov_b32 s8, 0
.Lsp_c_poll:
	s_nop 3
	global_load_dword v3, v5, s[6:7] sc1
	s_waitcnt vmcnt(0)
	v_cmp_ne_u32_e32 vcc, v3, v2
	s_cbranch_vccnz .Lsp_c_got
	s_add_i32 s8, s8, 1
	s_cmp_lt_u32 s8, 0x4000
	s_cbranch_scc0 .Lsp_c_got
	s_sleep 2
	s_branch .Lsp_c_poll
.Lsp_c_got:
	v_mov_b32_e32 v2, 0x230b4
	v_mov_b32_e32 v3, 0
	ds_write_b32 v2, v3
	s_waitcnt lgkmcnt(0)
.Lsp_c_skip:
	s_mov_b64 exec, s[4:5]
	s_waitcnt vmcnt(0) lgkmcnt(0)
	s_barrier
	buffer_inv sc1
.Lsp_done:
.LBB0_1077:
	v_readlane_b32 s4, v254, 54
	v_readlane_b32 s5, v254, 55
	s_andn2_b64 vcc, exec, s[4:5]
	v_readlane_b32 s4, v252, 59
	v_readlane_b32 s5, v252, 60
	s_nop 1
	v_cndmask_b32_e64 v0, 0, 1, s[4:5]
	v_cmp_ne_u32_e64 s[44:45], 1, v0
	s_cbranch_vccnz .LBB0_1185
	v_readfirstlane_b32 s36, v210
	s_lshr_b32 s55, s36, 6
	s_waitcnt lgkmcnt(0)
	s_mov_b64 s[28:29], s[94:95]
	s_and_b64 vcc, exec, s[44:45]
	s_cbranch_vccnz .LBB0_1109
	v_readlane_b32 s4, v252, 51
	v_readlane_b32 s5, v252, 52
	s_lshl_b64 s[4:5], s[4:5], 3
	s_add_u32 s4, s28, s4
	s_addc_u32 s5, s29, s5
	s_add_u32 s6, s28, 0xc400000
	s_addc_u32 s7, s29, 0
	s_add_u32 s8, s28, 0xd400000
	s_addc_u32 s9, s29, 0
	s_add_u32 s10, s28, 0x13400000
	s_addc_u32 s11, s29, 0
	s_add_u32 s12, s4, 0x40000
	s_addc_u32 s13, s5, 0
	s_lshl_b32 s14, s55, 1
	s_lshr_b32 s15, s36, 7
	s_and_b32 s16, s36, 0xffffffc0
	s_mov_b32 s17, s2
	s_branch .LBB0_1081
